# v74 + attention row-max chain head: canon(p1), canon(p0), max collapsed into one v_max_f32 per slice, bit-identical
# speedup vs baseline: 1.0008x; 1.0007x over previous
; template <int N> __device__ __forceinline__ void psm_slice(f32x16& p0, f32x16& p1, float& m_reg, float& alpha, PsmSt& st) {
;     if constexpr (N == 0) { float c = fmaxf(p0[0], p0[1]);
; #pragma unroll
;         for (int r = 2; r < 16; r += 2) c = fmaxf(fmaxf(c, p0[r]), p0[r + 1]);
;         st.c0 = c; }
;     else if constexpr (N == 1) { float c = fmaxf(p1[0], p1[1]);
; #pragma unroll
;         for (int r = 2; r < 16; r += 2) c = fmaxf(fmaxf(c, p1[r]), p1[r + 1]);
;         st.c1 = c; }
;     else if constexpr (N == 2) { float pmax = fmaxf(st.c0, st.c1);
;         auto rr = __builtin_amdgcn_permlane32_swap(__float_as_uint(pmax), __float_as_uint(pmax), false, false); pmax = fmaxf(__uint_as_float(rr[0]), __uint_as_float(rr[1]));
;         const bool keep = __all(pmax - m_reg <= THR2);
;         st.mn = keep ? m_reg : fmaxf(m_reg, pmax); }
;     else if constexpr (N == 3) { alpha = __builtin_amdgcn_exp2f(m_reg - st.mn); m_reg = st.mn; }
;     else if constexpr (N < 8) { constexpr int r = 2 * (N - 4); p0[r] = __builtin_amdgcn_exp2f(p0[r] - st.mn); p0[r + 1] = __builtin_amdgcn_exp2f(p0[r + 1] - st.mn); }
;     else { constexpr int r = N; p0[r] = __builtin_amdgcn_exp2f(p0[r] - st.mn); }
; template <bool PSM, bool PRE> __device__ __forceinline__ void region_pv(f32x16* o, int vb, const bf16x8 (&pa)[4], f32x16& pn0, f32x16& pn1, float& m_reg, float& alpha, s16x4 (&l)[4], s16x4 (&h)[4]) {
;     PsmSt st;
;     if constexpr (!PRE) {
;     l[0] = tr_read<v_rd_off(0, 0, 0)>(vb); h[0] = tr_read<v_rd_off(0, 0, 1)>(vb); l[1] = tr_read<v_rd_off(0, 1, 0)>(vb); h[1] = tr_read<v_rd_off(0, 1, 1)>(vb);
;     l[2] = tr_read<v_rd_off(0, 2, 0)>(vb); h[2] = tr_read<v_rd_off(0, 2, 1)>(vb); l[3] = tr_read<v_rd_off(0, 3, 0)>(vb); h[3] = tr_read<v_rd_off(0, 3, 1)>(vb);
;     SBAR(); }
;     sfor<0, 16>([&](auto n_) { constexpr int n = decltype(n_)::value, b = n >> 2, k = n & 3;
;         o[b] = __builtin_amdgcn_mfma_f32_32x32x16_bf16(pa[k], (bf16x8){l[k][0], l[k][1], l[k][2], l[k][3], h[k][0], h[k][1], h[k][2], h[k][3]}, o[b], 0, 0, 0);
;         if constexpr (b < 3) { l[k] = tr_read<v_rd_off((b + 1) & 3, k, 0)>(vb); h[k] = tr_read<v_rd_off((b + 1) & 3, k, 1)>(vb); }
;         if constexpr (PSM) psm_slice<n>(pn0, pn1, m_reg, alpha, st);
;         __builtin_amdgcn_sched_group_barrier(0x8, 1, 0); __builtin_amdgcn_sched_group_barrier(0x100, 2, 0);
;         SBAR();
;     });
.LBB0_624:
	s_waitcnt lgkmcnt(6)
	v_mfma_f32_32x32x16_bf16 v[0:15], v[64:67], v[100:103], v[0:15]
	v_max3_f32 v108, v110, v111, v112
	v_max3_f32 v108, v108, v113, v114
	ds_read_b64_tr_b16 v[100:101], v251 offset:512
	ds_read_b64_tr_b16 v[102:103], v251 offset:2560
	v_max3_f32 v108, v108, v115, v116
	v_max3_f32 v108, v108, v117, v118
	v_max3_f32 v108, v108, v119, v120
	v_max3_f32 v108, v108, v121, v122
	v_max3_f32 v108, v108, v123, v124
	s_waitcnt lgkmcnt(6)
	v_mfma_f32_32x32x16_bf16 v[0:15], v[68:71], v[126:129], v[0:15]
	v_max_f32_e32 v109, v80, v81
	v_max3_f32 v109, v109, v82, v83
	ds_read_b64_tr_b16 v[132:133], v251 offset:4608
	ds_read_b64_tr_b16 v[134:135], v251 offset:6656
	v_max3_f32 v109, v109, v84, v85
	v_max3_f32 v109, v109, v86, v87
	v_max3_f32 v109, v109, v88, v89
	v_max3_f32 v109, v109, v90, v91
	v_max3_f32 v109, v109, v92, v93
	v_max3_f32 v109, v109, v94, v95
	v_max3_f32 v108, v108, v125, v109
	v_mov_b32_e32 v109, v108
	s_waitcnt lgkmcnt(6)
	v_mfma_f32_32x32x16_bf16 v[0:15], v[72:75], v[104:107], v[0:15]
	v_permlane32_swap_b32_e32 v108, v109
	v_max_f32_e32 v108, v108, v109
	v_sub_f32_e32 v109, v108, v130
	ds_read_b64_tr_b16 v[104:105], v251 offset:8704
	ds_read_b64_tr_b16 v[106:107], v251 offset:10752
	v_cmp_ge_f32_e32 vcc, s33, v109
	s_cmp_eq_u64 vcc, exec
	s_cselect_b64 vcc, -1, 0
	v_max_f32_e32 v108, v130, v108
	v_cndmask_b32_e32 v252, v108, v130, vcc
	s_waitcnt lgkmcnt(6)
	v_mfma_f32_32x32x16_bf16 v[0:15], v[76:79], v[96:99], v[0:15]
	v_sub_f32_e32 v108, v130, v252
	ds_read_b64_tr_b16 v[96:97], v251 offset:12800
	ds_read_b64_tr_b16 v[98:99], v251 offset:14848
	v_exp_f32_e32 v227, v108
	s_waitcnt lgkmcnt(6)
	v_mfma_f32_32x32x16_bf16 v[48:63], v[64:67], v[100:103], v[48:63]
	v_sub_f32_e32 v108, v110, v252
	v_exp_f32_e32 v126, v108
	v_sub_f32_e32 v108, v111, v252
	ds_read_b64_tr_b16 v[100:101], v251 offset:1024
	ds_read_b64_tr_b16 v[102:103], v251 offset:3072
	v_exp_f32_e32 v127, v108
	s_waitcnt lgkmcnt(6)
	v_mfma_f32_32x32x16_bf16 v[48:63], v[68:71], v[132:135], v[48:63]
	v_sub_f32_e32 v112, v112, v252
	v_exp_f32_e32 v128, v112
	v_sub_f32_e32 v112, v113, v252
	ds_read_b64_tr_b16 v[108:109], v251 offset:5120
	ds_read_b64_tr_b16 v[110:111], v251 offset:7168
	v_exp_f32_e32 v129, v112
	s_waitcnt lgkmcnt(6)
	v_mfma_f32_32x32x16_bf16 v[48:63], v[72:75], v[104:107], v[48:63]
	v_sub_f32_e32 v112, v114, v252
	v_exp_f32_e32 v130, v112
	v_sub_f32_e32 v112, v115, v252
	ds_read_b64_tr_b16 v[104:105], v251 offset:9216
	ds_read_b64_tr_b16 v[106:107], v251 offset:11264
	v_exp_f32_e32 v131, v112
	s_waitcnt lgkmcnt(6)
	v_mfma_f32_32x32x16_bf16 v[48:63], v[76:79], v[96:99], v[48:63]
	v_sub_f32_e32 v112, v116, v252
	v_exp_f32_e32 v132, v112
	v_sub_f32_e32 v112, v117, v252
	ds_read_b64_tr_b16 v[96:97], v251 offset:13312
	ds_read_b64_tr_b16 v[98:99], v251 offset:15360
	v_exp_f32_e32 v133, v112
	s_waitcnt lgkmcnt(6)
	v_mfma_f32_32x32x16_bf16 v[32:47], v[64:67], v[100:103], v[32:47]
	v_sub_f32_e32 v112, v118, v252
	ds_read_b64_tr_b16 v[100:101], v251 offset:1536
	ds_read_b64_tr_b16 v[102:103], v251 offset:3584
	v_exp_f32_e32 v134, v112
	s_waitcnt lgkmcnt(6)
	v_mfma_f32_32x32x16_bf16 v[32:47], v[68:71], v[108:111], v[32:47]
	v_sub_f32_e32 v112, v119, v252
	ds_read_b64_tr_b16 v[108:109], v251 offset:5632
	ds_read_b64_tr_b16 v[110:111], v251 offset:7680
	v_exp_f32_e32 v135, v112
	s_waitcnt lgkmcnt(6)
	v_mfma_f32_32x32x16_bf16 v[32:47], v[72:75], v[104:107], v[32:47]
	v_sub_f32_e32 v112, v120, v252
	ds_read_b64_tr_b16 v[104:105], v251 offset:9728
	ds_read_b64_tr_b16 v[106:107], v251 offset:11776
	v_exp_f32_e32 v136, v112
	s_waitcnt lgkmcnt(6)
	v_mfma_f32_32x32x16_bf16 v[32:47], v[76:79], v[96:99], v[32:47]
	v_sub_f32_e32 v112, v121, v252
	ds_read_b64_tr_b16 v[96:97], v251 offset:13824
	ds_read_b64_tr_b16 v[98:99], v251 offset:15872
	v_exp_f32_e32 v137, v112
	s_waitcnt lgkmcnt(6)
	v_mfma_f32_32x32x16_bf16 v[16:31], v[64:67], v[100:103], v[16:31]
	v_sub_f32_e32 v64, v122, v252
	v_exp_f32_e32 v138, v64
	s_waitcnt lgkmcnt(4)
	v_mfma_f32_32x32x16_bf16 v[16:31], v[68:71], v[108:111], v[16:31]
	v_sub_f32_e32 v64, v123, v252
	v_exp_f32_e32 v139, v64
	s_waitcnt lgkmcnt(2)
	v_mfma_f32_32x32x16_bf16 v[16:31], v[72:75], v[104:107], v[16:31]
	v_sub_f32_e32 v64, v124, v252
	v_exp_f32_e32 v140, v64
	s_waitcnt lgkmcnt(0)
	v_mfma_f32_32x32x16_bf16 v[16:31], v[76:79], v[96:99], v[16:31]
	v_sub_f32_e32 v64, v125, v252
	v_exp_f32_e32 v141, v64
	v_cmp_gt_f32_e32 vcc, 1.0, v227
	s_cbranch_vccz .LBB0_628
	s_and_saveexec_b64 s[48:49], s[40:41]
	ds_write_b32 v215, v227 offset:128
	s_or_b64 exec, exec, s[48:49]
	s_waitcnt lgkmcnt(0)
	ds_read_b128 v[64:67], v250 offset:224
	ds_read_b128 v[68:71], v250 offset:192
	ds_read_b128 v[72:75], v250 offset:160
	ds_read_b128 v[76:79], v250 offset:128
	s_waitcnt lgkmcnt(3)
	v_pk_mul_f32 v[14:15], v[14:15], v[66:67]
	s_waitcnt lgkmcnt(2)
	v_pk_mul_f32 v[10:11], v[10:11], v[70:71]
	s_waitcnt lgkmcnt(1)
	v_pk_mul_f32 v[6:7], v[6:7], v[74:75]
	s_waitcnt lgkmcnt(0)
	v_pk_mul_f32 v[2:3], v[2:3], v[78:79]
	v_pk_mul_f32 v[12:13], v[12:13], v[64:65]
	v_pk_mul_f32 v[8:9], v[8:9], v[68:69]
	v_pk_mul_f32 v[4:5], v[4:5], v[72:73]
	v_pk_mul_f32 v[0:1], v[0:1], v[76:77]
	v_pk_mul_f32 v[62:63], v[62:63], v[66:67]
	v_pk_mul_f32 v[58:59], v[58:59], v[70:71]
	v_pk_mul_f32 v[54:55], v[54:55], v[74:75]
	v_pk_mul_f32 v[50:51], v[50:51], v[78:79]
	v_pk_mul_f32 v[60:61], v[60:61], v[64:65]
	v_pk_mul_f32 v[56:57], v[56:57], v[68:69]
	v_pk_mul_f32 v[52:53], v[52:53], v[72:73]
	v_pk_mul_f32 v[48:49], v[48:49], v[76:77]
	v_pk_mul_f32 v[46:47], v[46:47], v[66:67]
	v_pk_mul_f32 v[42:43], v[42:43], v[70:71]
	v_pk_mul_f32 v[38:39], v[38:39], v[74:75]
	v_pk_mul_f32 v[34:35], v[34:35], v[78:79]
	v_pk_mul_f32 v[44:45], v[44:45], v[64:65]
	v_pk_mul_f32 v[40:41], v[40:41], v[68:69]
	v_pk_mul_f32 v[36:37], v[36:37], v[72:73]
	v_pk_mul_f32 v[32:33], v[32:33], v[76:77]
	v_pk_mul_f32 v[30:31], v[30:31], v[66:67]
	v_pk_mul_f32 v[26:27], v[26:27], v[70:71]
	v_pk_mul_f32 v[22:23], v[22:23], v[74:75]
	v_pk_mul_f32 v[18:19], v[18:19], v[78:79]
	v_pk_mul_f32 v[28:29], v[28:29], v[64:65]
	v_pk_mul_f32 v[24:25], v[24:25], v[68:69]
	v_pk_mul_f32 v[20:21], v[20:21], v[72:73]
	v_pk_mul_f32 v[16:17], v[16:17], v[76:77]
	.p2align 6
; #define SBAR() __builtin_amdgcn_sched_barrier(0)
; template <int M> __device__ __forceinline__ void fin_slice(f32x16& p0, f32x16& p1, float mreg, float alpha, float& l_reg, FinSt& st, bf16x8 (&pa)[4]) {
;     if constexpr (M < 16) {
;         p1[M] = __builtin_amdgcn_exp2f(p1[M] - mreg);
;         if constexpr (M == 0) st.s0 = p0[0]; else st.s0 += p0[M];
;         if constexpr ((M & 1) == 0) st.c[M / 2] = cvt_pk_n(p0[M], p0[M + 1]);
;     } else if constexpr (M < 20) {
;         constexpr int k = M - 16;
;         if constexpr (k == 0) st.s1 = p1[0]; else st.s1 += p1[4 * k];
;         st.s1 += p1[4 * k + 1]; st.s1 += p1[4 * k + 2]; st.s1 += p1[4 * k + 3];
; template <bool FIN, bool PRE, int DM, class Dma> __device__ __forceinline__ void region_qk(f32x16& ps0, f32x16& ps1, const char* Ks, const bf16x8* qr, const char* qslot, const int (&kb)[4], ...
;     bf16x8 kf[2][2], qf[2]; FinSt st;
;     ...
;     QKT_RD(0, 0);
;     sfor<0, 12>([&](auto d_) { constexpr int d0 = decltype(d_)::value, cb = d0 & 1, nb = cb ^ 1;
;         if constexpr (d0 < 11) QKT_RD(d0 + 1, nb);
;         if constexpr (d0 == 0) ps0 = __builtin_amdgcn_mfma_f32_32x32x16_bf16(kf[cb][0], qf[cb], f32x16{}, 0, 0, 0);
;         else ps0 = __builtin_amdgcn_mfma_f32_32x32x16_bf16(kf[cb][0], qf[cb], ps0, 0, 0, 0);
;         if constexpr (FIN) fin_slice<2 * d0>(pf0, pf1, mreg, alpha, l_reg, st, pa);
;         if constexpr (PRE && d0 >= 10) { constexpr int k = 2 * (d0 - 10); l[k] = tr_read<v_rd_off(0, k, 0)>(vb); h[k] = tr_read<v_rd_off(0, k, 1)>(vb); }
;         __builtin_amdgcn_sched_group_barrier(0x100, 3, 0); __builtin_amdgcn_sched_group_barrier(0x8, 1, 0);
;         SBAR();
;         if constexpr (d0 == 0) ps1 = __builtin_amdgcn_mfma_f32_32x32x16_bf16(kf[cb][1], qf[cb], f32x16{}, 0, 0, 0);
;         else ps1 = __builtin_amdgcn_mfma_f32_32x32x16_bf16(kf[cb][1], qf[cb], ps1, 0, 0, 0);
;         if constexpr (FIN) fin_slice<2 * d0 + 1>(pf0, pf1, mreg, alpha, l_reg, st, pa);
;         if constexpr (PRE && d0 >= 10) { constexpr int k = 2 * (d0 - 10) + 1; l[k] = tr_read<v_rd_off(0, k, 0)>(vb); h[k] = tr_read<v_rd_off(0, k, 1)>(vb); }
;         if constexpr ((d0 & 1) == 0 && d0 < 10 && (DM == 1 || (DM == 2 && d0 >= 6))) dma(std::integral_constant<int, d0 / 2>{});
;         __builtin_amdgcn_sched_group_barrier(0x8, 1, 0);
;         SBAR();
;     });
.LBB0_628:
	s_waitcnt vmcnt(0)
	s_waitcnt lgkmcnt(0)
	s_barrier
	ds_read_b128 v[64:67], v242 offset:32768
	ds_read_b128 v[68:71], v242 offset:45056
	ds_read_b128 v[112:115], v244 offset:32768
	ds_read_b128 v[116:119], v244 offset:45056
	v_sub_f32_e32 v72, v80, v252
	v_exp_f32_e32 v194, v72
	v_cvt_pk_bf16_f32 v80, v126, v127
	s_waitcnt lgkmcnt(3)
	v_mfma_f32_32x32x16_bf16 v[96:111], v[64:67], v[186:189], 0
	s_waitcnt lgkmcnt(2)
	v_mfma_f32_32x32x16_bf16 v[64:79], v[68:71], v[186:189], 0
	s_add_u32 s48, s46, 1
	s_addc_u32 s49, s47, 0
	v_lshlrev_b64 v[120:121], v210, s[48:49]
	v_lshl_add_u64 v[120:121], v[120:121], 1, v[228:229]
	s_mov_b32 s12, m0
	s_mov_b32 m0, s66
	s_nop 0
	global_load_lds_dwordx4 v[120:121], off
	s_mov_b32 m0, s12
	v_sub_f32_e32 v81, v81, v252
	v_exp_f32_e32 v195, v81
	v_add_f32_e32 v81, v126, v127
	ds_read_b128 v[120:123], v246 offset:32768
	ds_read_b128 v[124:127], v246 offset:45056
	s_waitcnt lgkmcnt(3)
	v_mfma_f32_32x32x16_bf16 v[96:111], v[112:115], v[182:185], v[96:111]
	v_sub_f32_e32 v82, v82, v252
	v_exp_f32_e32 v196, v82
	v_add_f32_e32 v82, v128, v81
	v_cvt_pk_bf16_f32 v81, v128, v129
	s_waitcnt lgkmcnt(2)
	v_mfma_f32_32x32x16_bf16 v[64:79], v[116:119], v[182:185], v[64:79]
	v_sub_f32_e32 v83, v83, v252
	v_exp_f32_e32 v128, v83
	v_add_f32_e32 v82, v129, v82
	ds_read_b128 v[112:115], v248 offset:32768
	ds_read_b128 v[116:119], v248 offset:45056
	s_waitcnt lgkmcnt(3)
	v_mfma_f32_32x32x16_bf16 v[96:111], v[120:123], v[178:181], v[96:111]
	v_sub_f32_e32 v83, v84, v252
	v_exp_f32_e32 v129, v83
	v_add_f32_e32 v83, v130, v82
	v_cvt_pk_bf16_f32 v82, v130, v131
	s_waitcnt lgkmcnt(2)
	v_mfma_f32_32x32x16_bf16 v[64:79], v[124:127], v[178:181], v[64:79]
	v_sub_f32_e32 v84, v85, v252
	v_exp_f32_e32 v130, v84
	v_lshlrev_b64 v[84:85], v212, s[48:49]
	v_lshl_add_u64 v[84:85], v[84:85], 1, v[230:231]
	s_mov_b32 s12, m0
	s_mov_b32 m0, s67
	s_nop 0
	global_load_lds_dwordx4 v[84:85], off
	s_mov_b32 m0, s12
	v_add_f32_e32 v83, v131, v83
	ds_read_b128 v[120:123], v242 offset:32896
	ds_read_b128 v[124:127], v242 offset:45184
	s_waitcnt lgkmcnt(3)
	v_mfma_f32_32x32x16_bf16 v[96:111], v[112:115], v[174:177], v[96:111]
	v_sub_f32_e32 v84, v86, v252
	v_exp_f32_e32 v131, v84
	v_add_f32_e32 v84, v132, v83
	v_cvt_pk_bf16_f32 v83, v132, v133
	s_waitcnt lgkmcnt(2)
	v_mfma_f32_32x32x16_bf16 v[64:79], v[116:119], v[174:177], v[64:79]
	v_sub_f32_e32 v85, v87, v252
	v_exp_f32_e32 v132, v85
	v_add_f32_e32 v84, v133, v84
	ds_read_b128 v[112:115], v244 offset:32896
	ds_read_b128 v[116:119], v244 offset:45184
	s_waitcnt lgkmcnt(3)
	v_mfma_f32_32x32x16_bf16 v[96:111], v[120:123], v[170:173], v[96:111]
	v_sub_f32_e32 v85, v88, v252
	v_exp_f32_e32 v133, v85
	v_add_f32_e32 v85, v134, v84
	v_cvt_pk_bf16_f32 v84, v134, v135
	s_waitcnt lgkmcnt(2)
	v_mfma_f32_32x32x16_bf16 v[64:79], v[124:127], v[170:173], v[64:79]
	v_sub_f32_e32 v86, v89, v252
	v_exp_f32_e32 v126, v86
	v_lshlrev_b64 v[86:87], v214, s[48:49]
	v_lshl_add_u64 v[86:87], v[86:87], 1, v[232:233]
	s_mov_b32 s12, m0
	s_mov_b32 m0, s68
	s_nop 0
	global_load_lds_dwordx4 v[86:87], off
	s_mov_b32 m0, s12
	v_add_f32_e32 v85, v135, v85
	ds_read_b128 v[86:89], v246 offset:32896
	ds_read_b128 v[120:123], v246 offset:45184
	s_waitcnt lgkmcnt(3)
	v_mfma_f32_32x32x16_bf16 v[96:111], v[112:115], v[166:169], v[96:111]
	v_sub_f32_e32 v90, v90, v252
	v_exp_f32_e32 v127, v90
	v_add_f32_e32 v90, v136, v85
	v_cvt_pk_bf16_f32 v85, v136, v137
	s_waitcnt lgkmcnt(2)
	v_mfma_f32_32x32x16_bf16 v[64:79], v[116:119], v[166:169], v[64:79]
	v_sub_f32_e32 v91, v91, v252
	v_exp_f32_e32 v134, v91
	v_add_f32_e32 v90, v137, v90
	ds_read_b128 v[112:115], v248 offset:32896
	ds_read_b128 v[116:119], v248 offset:45184
	s_waitcnt lgkmcnt(3)
	v_mfma_f32_32x32x16_bf16 v[96:111], v[86:89], v[162:165], v[96:111]
	v_sub_f32_e32 v86, v92, v252
	v_exp_f32_e32 v135, v86
	v_add_f32_e32 v87, v138, v90
	v_cvt_pk_bf16_f32 v86, v138, v139
	s_waitcnt lgkmcnt(2)
	v_mfma_f32_32x32x16_bf16 v[64:79], v[120:123], v[162:165], v[64:79]
	s_mov_b32 s12, m0
	s_mov_b32 m0, s69
	s_nop 0
	global_load_lds_dwordx4 v211, s[42:43]
	s_mov_b32 m0, s12
	v_sub_f32_e32 v88, v93, v252
	v_exp_f32_e32 v136, v88
	v_add_f32_e32 v87, v139, v87
	ds_read_b128 v[88:91], v242 offset:33024
	ds_read_b128 v[120:123], v242 offset:45312
	s_waitcnt lgkmcnt(3)
	v_mfma_f32_32x32x16_bf16 v[96:111], v[112:115], v[158:161], v[96:111]
	v_sub_f32_e32 v92, v94, v252
	v_exp_f32_e32 v137, v92
	v_add_f32_e32 v92, v140, v87
	v_cvt_pk_bf16_f32 v87, v140, v141
	s_waitcnt lgkmcnt(2)
	v_mfma_f32_32x32x16_bf16 v[64:79], v[116:119], v[158:161], v[64:79]
	v_sub_f32_e32 v93, v95, v252
	v_exp_f32_e32 v138, v93
	v_add_f32_e32 v139, v141, v92
	ds_read_b128 v[92:95], v244 offset:33024
	ds_read_b128 v[114:117], v244 offset:45312
	s_waitcnt lgkmcnt(3)
	v_mfma_f32_32x32x16_bf16 v[96:111], v[88:91], v[154:157], v[96:111]
	v_add_f32_e32 v88, v194, v195
	v_add_f32_e32 v88, v196, v88
	v_add_f32_e32 v90, v128, v88
	v_cvt_pk_bf16_f32 v88, v194, v195
	v_cvt_pk_bf16_f32 v89, v196, v128
	v_permlane32_swap_b32_e32 v80, v82
	v_permlane32_swap_b32_e32 v81, v83
	s_waitcnt lgkmcnt(2)
	v_mfma_f32_32x32x16_bf16 v[64:79], v[120:123], v[154:157], v[64:79]
	v_add_f32_e32 v90, v129, v90
	s_mov_b32 s12, m0
	s_mov_b32 m0, s70
	s_nop 0
	global_load_lds_dwordx4 v213, s[42:43]
	s_mov_b32 m0, s12
	v_add_f32_e32 v90, v130, v90
	v_add_f32_e32 v90, v131, v90
	v_add_f32_e32 v112, v132, v90
	v_cvt_pk_bf16_f32 v90, v129, v130
	v_cvt_pk_bf16_f32 v91, v131, v132
	v_permlane32_swap_b32_e32 v84, v86
	v_permlane32_swap_b32_e32 v85, v87
	ds_read_b128 v[118:121], v246 offset:33024
	ds_read_b128 v[122:125], v246 offset:45312
	s_waitcnt lgkmcnt(3)
; template <int N> __device__ __forceinline__ void psm_slice(f32x16& p0, f32x16& p1, float& m_reg, float& alpha, PsmSt& st) {
;     if constexpr (N == 0) { float c = fmaxf(p0[0], p0[1]);
; #pragma unroll
;         for (int r = 2; r < 16; r += 2) c = fmaxf(fmaxf(c, p0[r]), p0[r + 1]);
;         st.c0 = c; }
;     else if constexpr (N == 1) { float c = fmaxf(p1[0], p1[1]);
; #pragma unroll
;         for (int r = 2; r < 16; r += 2) c = fmaxf(fmaxf(c, p1[r]), p1[r + 1]);
;         st.c1 = c; }
;     else if constexpr (N == 2) { float pmax = fmaxf(st.c0, st.c1);
;         auto rr = __builtin_amdgcn_permlane32_swap(__float_as_uint(pmax), __float_as_uint(pmax), false, false); pmax = fmaxf(__uint_as_float(rr[0]), __uint_as_float(rr[1]));
;         const bool keep = __all(pmax - m_reg <= THR2);
;         st.mn = keep ? m_reg : fmaxf(m_reg, pmax); }
;     else if constexpr (N == 3) { alpha = __builtin_amdgcn_exp2f(m_reg - st.mn); m_reg = st.mn; }
;     else if constexpr (N < 8) { constexpr int r = 2 * (N - 4); p0[r] = __builtin_amdgcn_exp2f(p0[r] - st.mn); p0[r + 1] = __builtin_amdgcn_exp2f(p0[r + 1] - st.mn); }
;     else { constexpr int r = N; p0[r] = __builtin_amdgcn_exp2f(p0[r] - st.mn); }
; }
; template <int M> __device__ __forceinline__ void fin_slice(f32x16& p0, f32x16& p1, float mreg, float alpha, float& l_reg, FinSt& st, bf16x8 (&pa)[4]) {
;     if constexpr (M < 16) {
;         p1[M] = __builtin_amdgcn_exp2f(p1[M] - mreg);
;         if constexpr (M == 0) st.s0 = p0[0]; else st.s0 += p0[M];
;         if constexpr ((M & 1) == 0) st.c[M / 2] = cvt_pk_n(p0[M], p0[M + 1]);
;     } else if constexpr (M < 20) {
;         constexpr int k = M - 16;
;         if constexpr (k == 0) st.s1 = p1[0]; else st.s1 += p1[4 * k];
;         st.s1 += p1[4 * k + 1]; st.s1 += p1[4 * k + 2]; st.s1 += p1[4 * k + 3];
;         st.c[8 + 2 * k] = cvt_pk_n(p1[4 * k], p1[4 * k + 1]); st.c[9 + 2 * k] = cvt_pk_n(p1[4 * k + 2], p1[4 * k + 3]);
;         if constexpr (k == 0) pa[0] = pk_swz(st.c[0], st.c[1], st.c[2], st.c[3]);
;         if constexpr (k == 1) pa[1] = pk_swz(st.c[4], st.c[5], st.c[6], st.c[7]);
;     } else if constexpr (M == 20) pa[2] = pk_swz(st.c[8], st.c[9], st.c[10], st.c[11]);
;     else if constexpr (M == 21) pa[3] = pk_swz(st.c[12], st.c[13], st.c[14], st.c[15]);
;     else if constexpr (M == 22) { float ps = st.s0 + st.s1;
	v_mfma_f32_32x32x16_bf16 v[96:111], v[92:95], v[150:153], v[96:111]
	v_add_f32_e32 v92, v133, v112
	v_add_f32_e32 v92, v126, v92
	v_add_f32_e32 v92, v127, v92
	v_add_f32_e32 v92, v134, v92
	v_cvt_pk_bf16_f32 v112, v133, v126
	v_cvt_pk_bf16_f32 v113, v127, v134
	s_waitcnt lgkmcnt(2)
	v_mfma_f32_32x32x16_bf16 v[64:79], v[114:117], v[150:153], v[64:79]
	v_add_f32_e32 v92, v135, v92
	v_add_f32_e32 v92, v136, v92
	v_add_f32_e32 v92, v137, v92
	v_add_f32_e32 v130, v138, v92
	v_cvt_pk_bf16_f32 v114, v135, v136
	v_cvt_pk_bf16_f32 v115, v137, v138
	ds_read_b128 v[92:95], v248 offset:33024
	ds_read_b128 v[126:129], v248 offset:45312
	ds_read_b64_tr_b16 v[116:117], v251 offset:16384
	s_waitcnt lgkmcnt(4)
	v_mfma_f32_32x32x16_bf16 v[96:111], v[118:121], v[146:149], v[96:111]
	ds_read_b64_tr_b16 v[118:119], v251 offset:18432
	v_permlane32_swap_b32_e32 v88, v90
	v_permlane32_swap_b32_e32 v89, v91
	s_waitcnt lgkmcnt(4)
	v_mfma_f32_32x32x16_bf16 v[64:79], v[122:125], v[146:149], v[64:79]
	ds_read_b64_tr_b16 v[120:121], v251 offset:20480
	ds_read_b64_tr_b16 v[122:123], v251 offset:22528
	v_permlane32_swap_b32_e32 v112, v114
	v_permlane32_swap_b32_e32 v113, v115
	ds_read_b64_tr_b16 v[132:133], v251 offset:26624
	s_waitcnt lgkmcnt(6)
	v_mfma_f32_32x32x16_bf16 v[96:111], v[92:95], v[142:145], v[96:111]
	v_add_f32_e32 v92, v139, v130
	ds_read_b64_tr_b16 v[130:131], v251 offset:24576
	v_mov_b32_e32 v93, v92
	s_nop 1
	v_permlane32_swap_b32_e32 v92, v93
	s_waitcnt lgkmcnt(6)
	v_mfma_f32_32x32x16_bf16 v[64:79], v[126:129], v[142:145], v[64:79]
	ds_read_b64_tr_b16 v[124:125], v251 offset:28672
	ds_read_b64_tr_b16 v[126:127], v251 offset:30720
	s_waitcnt lgkmcnt(6)
	v_mfma_f32_32x32x16_bf16 v[0:15], v[80:83], v[116:119], v[0:15]
	v_max3_f32 v94, v96, v97, v98
	v_max3_f32 v94, v94, v99, v100
	v_max3_f32 v94, v94, v101, v102
	ds_read_b64_tr_b16 v[116:117], v251 offset:16896
	ds_read_b64_tr_b16 v[118:119], v251 offset:18944
	v_max3_f32 v94, v94, v103, v104
	v_max3_f32 v94, v94, v105, v106
	v_max3_f32 v94, v94, v107, v108
	v_max3_f32 v94, v94, v109, v110
	s_waitcnt lgkmcnt(6)
	v_mfma_f32_32x32x16_bf16 v[0:15], v[84:87], v[120:123], v[0:15]
	v_max_f32_e32 v95, v64, v65
	v_max3_f32 v95, v95, v66, v67
	v_max3_f32 v95, v95, v68, v69
	v_max3_f32 v95, v95, v70, v71
	ds_read_b64_tr_b16 v[120:121], v251 offset:20992
	ds_read_b64_tr_b16 v[122:123], v251 offset:23040
	v_max3_f32 v95, v95, v72, v73
	v_max3_f32 v95, v95, v74, v75
	v_max3_f32 v95, v95, v76, v77
	v_max3_f32 v95, v95, v78, v79
	v_max3_f32 v94, v94, v111, v95
	v_mov_b32_e32 v95, v94
	s_waitcnt lgkmcnt(6)
	v_mfma_f32_32x32x16_bf16 v[0:15], v[88:91], v[130:133], v[0:15]
	v_permlane32_swap_b32_e32 v94, v95
	v_max_f32_e32 v94, v94, v95
	v_sub_f32_e32 v95, v94, v252
	ds_read_b64_tr_b16 v[132:133], v251 offset:25088
	ds_read_b64_tr_b16 v[134:135], v251 offset:27136
	v_cmp_ge_f32_e32 vcc, s33, v95
	s_cmp_eq_u64 vcc, exec
	s_cselect_b64 vcc, -1, 0
	v_max_f32_e32 v94, v252, v94
	v_cndmask_b32_e32 v130, v94, v252, vcc
	s_waitcnt lgkmcnt(6)
	v_mfma_f32_32x32x16_bf16 v[0:15], v[112:115], v[124:127], v[0:15]
	v_sub_f32_e32 v94, v252, v130
	ds_read_b64_tr_b16 v[124:125], v251 offset:29184
	ds_read_b64_tr_b16 v[126:127], v251 offset:31232
	v_exp_f32_e32 v131, v94
	s_waitcnt lgkmcnt(6)
	v_mfma_f32_32x32x16_bf16 v[48:63], v[80:83], v[116:119], v[48:63]
	v_sub_f32_e32 v94, v96, v130
	v_sub_f32_e32 v95, v97, v130
	ds_read_b64_tr_b16 v[116:117], v251 offset:17408
	ds_read_b64_tr_b16 v[118:119], v251 offset:19456
	v_exp_f32_e32 v94, v94
	v_exp_f32_e32 v95, v95
	s_waitcnt lgkmcnt(6)
	v_mfma_f32_32x32x16_bf16 v[48:63], v[84:87], v[120:123], v[48:63]
	v_sub_f32_e32 v96, v98, v130
	v_sub_f32_e32 v97, v99, v130
	ds_read_b64_tr_b16 v[120:121], v251 offset:21504
	ds_read_b64_tr_b16 v[122:123], v251 offset:23552
	v_exp_f32_e32 v96, v96
	v_exp_f32_e32 v97, v97
	s_waitcnt lgkmcnt(6)
	v_mfma_f32_32x32x16_bf16 v[48:63], v[88:91], v[132:135], v[48:63]
	v_sub_f32_e32 v98, v100, v130
	v_sub_f32_e32 v99, v101, v130
	ds_read_b64_tr_b16 v[132:133], v251 offset:25600
	ds_read_b64_tr_b16 v[134:135], v251 offset:27648
	v_exp_f32_e32 v98, v98
	v_exp_f32_e32 v99, v99
	s_waitcnt lgkmcnt(6)
	v_mfma_f32_32x32x16_bf16 v[48:63], v[112:115], v[124:127], v[48:63]
	v_sub_f32_e32 v100, v102, v130
	v_sub_f32_e32 v101, v103, v130
	ds_read_b64_tr_b16 v[124:125], v251 offset:29696
	ds_read_b64_tr_b16 v[126:127], v251 offset:31744
	v_exp_f32_e32 v100, v100
	v_exp_f32_e32 v101, v101
	s_waitcnt lgkmcnt(6)
	v_mfma_f32_32x32x16_bf16 v[32:47], v[80:83], v[116:119], v[32:47]
	v_sub_f32_e32 v102, v104, v130
	ds_read_b64_tr_b16 v[116:117], v251 offset:17920
	ds_read_b64_tr_b16 v[118:119], v251 offset:19968
	v_exp_f32_e32 v102, v102
	s_waitcnt lgkmcnt(6)
	v_mfma_f32_32x32x16_bf16 v[32:47], v[84:87], v[120:123], v[32:47]
	v_sub_f32_e32 v103, v105, v130
	ds_read_b64_tr_b16 v[120:121], v251 offset:22016
	ds_read_b64_tr_b16 v[122:123], v251 offset:24064
	v_exp_f32_e32 v103, v103
	s_waitcnt lgkmcnt(6)
	v_mfma_f32_32x32x16_bf16 v[32:47], v[88:91], v[132:135], v[32:47]
	v_sub_f32_e32 v104, v106, v130
	ds_read_b64_tr_b16 v[132:133], v251 offset:26112
	ds_read_b64_tr_b16 v[134:135], v251 offset:28160
	v_exp_f32_e32 v104, v104
	s_waitcnt lgkmcnt(6)
	v_mfma_f32_32x32x16_bf16 v[32:47], v[112:115], v[124:127], v[32:47]
	v_sub_f32_e32 v105, v107, v130
	ds_read_b64_tr_b16 v[124:125], v251 offset:30208
	ds_read_b64_tr_b16 v[126:127], v251 offset:32256
	v_exp_f32_e32 v105, v105
	s_waitcnt lgkmcnt(6)
	v_mfma_f32_32x32x16_bf16 v[16:31], v[80:83], v[116:119], v[16:31]
	v_sub_f32_e32 v80, v108, v130
	v_exp_f32_e32 v106, v80
	s_waitcnt lgkmcnt(4)
	v_mfma_f32_32x32x16_bf16 v[16:31], v[84:87], v[120:123], v[16:31]
	v_sub_f32_e32 v80, v109, v130
	v_exp_f32_e32 v107, v80
	s_waitcnt lgkmcnt(2)
	v_mfma_f32_32x32x16_bf16 v[16:31], v[88:91], v[132:135], v[16:31]
	v_sub_f32_e32 v80, v110, v130
	v_exp_f32_e32 v108, v80
	s_waitcnt lgkmcnt(0)
	v_mfma_f32_32x32x16_bf16 v[16:31], v[112:115], v[124:127], v[16:31]
	v_sub_f32_e32 v80, v111, v130
	v_exp_f32_e32 v109, v80
	v_cmp_gt_f32_e32 vcc, 1.0, v131
	s_cbranch_vccz .LBB0_632
	s_and_saveexec_b64 s[48:49], s[40:41]
	ds_write_b32 v215, v131 offset:128
	s_or_b64 exec, exec, s[48:49]
	s_waitcnt lgkmcnt(0)
	ds_read_b128 v[80:83], v250 offset:224
	ds_read_b128 v[84:87], v250 offset:192
	ds_read_b128 v[88:91], v250 offset:160
	ds_read_b128 v[110:113], v250 offset:128
	s_waitcnt lgkmcnt(3)
	v_pk_mul_f32 v[14:15], v[14:15], v[82:83]
	s_waitcnt lgkmcnt(2)
	v_pk_mul_f32 v[10:11], v[10:11], v[86:87]
	s_waitcnt lgkmcnt(1)
	v_pk_mul_f32 v[6:7], v[6:7], v[90:91]
	s_waitcnt lgkmcnt(0)
	v_pk_mul_f32 v[2:3], v[2:3], v[112:113]
	v_pk_mul_f32 v[12:13], v[12:13], v[80:81]
	v_pk_mul_f32 v[8:9], v[8:9], v[84:85]
	v_pk_mul_f32 v[4:5], v[4:5], v[88:89]
	v_pk_mul_f32 v[0:1], v[0:1], v[110:111]
	v_pk_mul_f32 v[62:63], v[62:63], v[82:83]
	v_pk_mul_f32 v[58:59], v[58:59], v[86:87]
	v_pk_mul_f32 v[54:55], v[54:55], v[90:91]
	v_pk_mul_f32 v[50:51], v[50:51], v[112:113]
	v_pk_mul_f32 v[60:61], v[60:61], v[80:81]
	v_pk_mul_f32 v[56:57], v[56:57], v[84:85]
	v_pk_mul_f32 v[52:53], v[52:53], v[88:89]
	v_pk_mul_f32 v[48:49], v[48:49], v[110:111]
	v_pk_mul_f32 v[46:47], v[46:47], v[82:83]
	v_pk_mul_f32 v[42:43], v[42:43], v[86:87]
	v_pk_mul_f32 v[38:39], v[38:39], v[90:91]
	v_pk_mul_f32 v[34:35], v[34:35], v[112:113]
	v_pk_mul_f32 v[44:45], v[44:45], v[80:81]
	v_pk_mul_f32 v[40:41], v[40:41], v[84:85]
	v_pk_mul_f32 v[36:37], v[36:37], v[88:89]
	v_pk_mul_f32 v[32:33], v[32:33], v[110:111]
	v_pk_mul_f32 v[30:31], v[30:31], v[82:83]
	v_pk_mul_f32 v[26:27], v[26:27], v[86:87]
	v_pk_mul_f32 v[22:23], v[22:23], v[90:91]
	v_pk_mul_f32 v[18:19], v[18:19], v[112:113]
	v_pk_mul_f32 v[28:29], v[28:29], v[80:81]
	v_pk_mul_f32 v[24:25], v[24:25], v[84:85]
	v_pk_mul_f32 v[20:21], v[20:21], v[88:89]
	v_pk_mul_f32 v[16:17], v[16:17], v[110:111]
	.p2align 6
